# up epilogue: H store addresses use SGPR base + one 32-bit per-lane offset (scalar adds per store) instead of 64-bit VALU multiply/adds per store
# baseline (speedup 1.0000x reference)
; __device__ __forceinline__ unsigned cvt_pk_bf16(float lo, float hi) { unsigned r; asm volatile("v_cvt_pk_bf16_f32 %0, %1, %2" : "=v"(r) : "v"(lo), "v"(hi)); return r; }
;     __device__ __forceinline__ void operator()(const f32x4 (&acc)[2][2][4][2], const Unit& u, int ui, int wr, int wc, int fr, int fq) const {
;     ...
;         const int row0 = u.pm * BM + wr * 64 + fr, col0 = u.pn * HALF + wc * 32 + 8 * fq;
;         float rs[2][4];
; #pragma unroll
;         for (int ai = 0; ai < 2; ++ai)
; #pragma unroll
;             for (int m = 0; m < 4; ++m) rs[ai][m] = row_rstd(lds, ui, ai * HALF + wr * 64 + m * 16 + fr);
; #pragma unroll
;         for (int ai = 0; ai < 2; ++ai)
; #pragma unroll
;             for (int m = 0; m < 4; ++m) { const float r = rs[ai][m]; const int row = row0 + ai * HALF + m * 16;
;                 const float c1 = r * -1.44269504089f, r2 = r * r; u32x4 w;
; #pragma unroll
;                 for (int n = 0; n < 2; ++n)
; #pragma unroll
;                     for (int p = 0; p < 2; ++p) { const f32x2 g = (f32x2){acc[ai][0][m][n][2 * p], acc[ai][0][m][n][2 * p + 1]}, uu = (f32x2){acc[ai][1][m][n][2 * p], acc[ai][1][m][n][2 * p + 1]};
;                         const f32x2 t = g * c1; f32x2 d; d.x = __builtin_amdgcn_exp2f(t.x); d.y = __builtin_amdgcn_exp2f(t.y); d = d + 1.0f;
;                         f32x2 q; q.x = __builtin_amdgcn_rcpf(d.x); q.y = __builtin_amdgcn_rcpf(d.y);
;                         const f32x2 hh = (g * uu) * (q * r2); w[2 * n + p] = cvt_pk_bf16(hh.x, hh.y); }
;                 __builtin_nontemporal_store(w, (u32x4*)(H + (size_t)row * ldh + col0)); }
.LBB0_449:
	v_mov_b32_e32 v140, v147
	v_mov_b32_e32 v167, v164
	v_pk_mul_f32 v[120:121], v[124:125], v[120:121]
	v_add_u32_e32 v171, s35, v140
	v_lshlrev_b32_e32 v140, 2, v171
	v_lshl_add_u32 v140, s48, 10, v140
	v_add_u32_e32 v140, 0x20400, v140
	ds_read2_b32 v[168:169], v140 offset1:16
	ds_read2_b32 v[162:163], v140 offset0:32 offset1:48
	ds_read2_b32 v[142:143], v140 offset0:128 offset1:144
	ds_read2_b32 v[140:141], v140 offset0:160 offset1:176
	v_pk_mul_f32 v[122:123], v[126:127], v[122:123]
	s_waitcnt lgkmcnt(0)
	v_mul_f32_e32 v172, 0xbfb8aa3b, v168
	v_pk_mul_f32 v[174:175], v[124:125], v[172:173] op_sel_hi:[1,0]
	v_pk_mul_f32 v[124:125], v[126:127], v[172:173] op_sel_hi:[1,0]
	v_exp_f32_e32 v174, v174
	v_exp_f32_e32 v175, v175
	v_exp_f32_e32 v124, v124
	v_exp_f32_e32 v125, v125
	v_mul_f32_e32 v168, v168, v168
	v_pk_add_f32 v[174:175], v[174:175], 1.0 op_sel_hi:[1,0]
	v_pk_mul_f32 v[112:113], v[116:117], v[112:113]
	v_rcp_f32_e32 v174, v174
	v_rcp_f32_e32 v175, v175
	v_pk_add_f32 v[124:125], v[124:125], 1.0 op_sel_hi:[1,0]
	v_pk_mul_f32 v[114:115], v[118:119], v[114:115]
	v_rcp_f32_e32 v124, v124
	v_rcp_f32_e32 v125, v125
	v_pk_mul_f32 v[126:127], v[168:169], v[174:175] op_sel_hi:[0,1]
	v_pk_mul_f32 v[120:121], v[120:121], v[126:127]
	v_pk_mul_f32 v[126:127], v[116:117], v[172:173] op_sel_hi:[1,0]
	v_pk_mul_f32 v[124:125], v[168:169], v[124:125] op_sel_hi:[0,1]
	v_exp_f32_e32 v126, v126
	v_exp_f32_e32 v127, v127
	v_pk_mul_f32 v[122:123], v[122:123], v[124:125]
	v_pk_mul_f32 v[124:125], v[118:119], v[172:173] op_sel_hi:[1,0]
	v_cvt_pk_bf16_f32 v120, v120, v121
	v_cvt_pk_bf16_f32 v121, v122, v123
	v_pk_add_f32 v[122:123], v[126:127], 1.0 op_sel_hi:[1,0]
	v_exp_f32_e32 v124, v124
	v_exp_f32_e32 v125, v125
	v_rcp_f32_e32 v122, v122
	v_rcp_f32_e32 v123, v123
	s_lshl_b32 s5, s47, 7
	v_pk_add_f32 v[116:117], v[124:125], 1.0 op_sel_hi:[1,0]
	s_or_b32 s5, s5, s36
	v_rcp_f32_e32 v116, v116
	v_rcp_f32_e32 v117, v117
	v_pk_mul_f32 v[118:119], v[168:169], v[122:123] op_sel_hi:[0,1]
	v_pk_mul_f32 v[112:113], v[112:113], v[118:119]
	v_mul_f32_e32 v118, 0xbfb8aa3b, v169
	v_cvt_pk_bf16_f32 v122, v112, v113
	v_pk_mul_f32 v[112:113], v[168:169], v[116:117] op_sel_hi:[0,1]
	v_pk_mul_f32 v[124:125], v[108:109], v[118:119] op_sel_hi:[1,0]
	v_lshl_add_u32 v170, v167, 3, s5
	v_pk_mul_f32 v[112:113], v[114:115], v[112:113]
	v_exp_f32_e32 v124, v124
	v_exp_f32_e32 v125, v125
	v_lshl_add_u32 v167, s46, 8, v171
	v_mul_lo_u32 v255, v167, s59
	v_lshl_add_u32 v255, v170, 1, v255
	v_cvt_pk_bf16_f32 v123, v112, v113
	v_pk_mul_f32 v[104:105], v[108:109], v[104:105]
	v_pk_mul_f32 v[108:109], v[110:111], v[118:119] op_sel_hi:[1,0]
	v_exp_f32_e32 v108, v108
	v_exp_f32_e32 v109, v109
	s_add_u32 s100, s20, 0x0
	s_addc_u32 s101, s21, 0
	global_store_dwordx4 v255, v[120:123], s[100:101] nt
	v_mul_f32_e32 v116, v169, v169
	v_pk_add_f32 v[108:109], v[108:109], 1.0 op_sel_hi:[1,0]
	v_pk_add_f32 v[120:121], v[124:125], 1.0 op_sel_hi:[1,0]
	v_rcp_f32_e32 v108, v108
	v_rcp_f32_e32 v120, v120
	v_rcp_f32_e32 v121, v121
	v_rcp_f32_e32 v109, v109
	v_pk_mul_f32 v[106:107], v[110:111], v[106:107]
	v_pk_mul_f32 v[96:97], v[100:101], v[96:97]
	v_pk_mul_f32 v[110:111], v[116:117], v[120:121] op_sel_hi:[0,1]
	v_pk_mul_f32 v[104:105], v[104:105], v[110:111]
	v_pk_mul_f32 v[110:111], v[100:101], v[118:119] op_sel_hi:[1,0]
	v_pk_mul_f32 v[108:109], v[116:117], v[108:109] op_sel_hi:[0,1]
	v_exp_f32_e32 v110, v110
	v_exp_f32_e32 v111, v111
	v_pk_mul_f32 v[106:107], v[106:107], v[108:109]
	v_pk_mul_f32 v[108:109], v[102:103], v[118:119] op_sel_hi:[1,0]
	v_cvt_pk_bf16_f32 v104, v104, v105
	v_cvt_pk_bf16_f32 v105, v106, v107
	v_pk_add_f32 v[106:107], v[110:111], 1.0 op_sel_hi:[1,0]
	v_exp_f32_e32 v108, v108
	v_exp_f32_e32 v109, v109
	v_rcp_f32_e32 v106, v106
	v_rcp_f32_e32 v107, v107
	v_pk_mul_f32 v[98:99], v[102:103], v[98:99]
	v_pk_add_f32 v[100:101], v[108:109], 1.0 op_sel_hi:[1,0]
	v_pk_mul_f32 v[88:89], v[92:93], v[88:89]
	v_rcp_f32_e32 v100, v100
	v_rcp_f32_e32 v101, v101
	v_pk_mul_f32 v[102:103], v[116:117], v[106:107] op_sel_hi:[0,1]
	v_pk_mul_f32 v[96:97], v[96:97], v[102:103]
	v_pk_mul_f32 v[90:91], v[94:95], v[90:91]
	v_cvt_pk_bf16_f32 v106, v96, v97
	v_pk_mul_f32 v[96:97], v[116:117], v[100:101] op_sel_hi:[0,1]
	v_pk_mul_f32 v[96:97], v[98:99], v[96:97]
	v_mul_f32_e32 v98, 0xbfb8aa3b, v162
	v_pk_mul_f32 v[100:101], v[92:93], v[98:99] op_sel_hi:[1,0]
	v_pk_mul_f32 v[92:93], v[94:95], v[98:99] op_sel_hi:[1,0]
	v_exp_f32_e32 v100, v100
	v_exp_f32_e32 v101, v101
	v_exp_f32_e32 v92, v92
	v_exp_f32_e32 v93, v93
	v_cvt_pk_bf16_f32 v107, v96, v97
	v_pk_add_f32 v[100:101], v[100:101], 1.0 op_sel_hi:[1,0]
	v_rcp_f32_e32 v100, v100
	v_rcp_f32_e32 v101, v101
	v_pk_add_f32 v[92:93], v[92:93], 1.0 op_sel_hi:[1,0]
	v_rcp_f32_e32 v92, v92
	v_rcp_f32_e32 v93, v93
	s_add_u32 s100, s20, 0x16000
	s_addc_u32 s101, s21, 0
	global_store_dwordx4 v255, v[104:107], s[100:101] nt
	v_mul_f32_e32 v96, v162, v162
	v_pk_mul_f32 v[94:95], v[96:97], v[100:101] op_sel_hi:[0,1]
	v_pk_mul_f32 v[88:89], v[88:89], v[94:95]
	v_pk_mul_f32 v[94:95], v[84:85], v[98:99] op_sel_hi:[1,0]
	v_pk_mul_f32 v[92:93], v[96:97], v[92:93] op_sel_hi:[0,1]
	v_exp_f32_e32 v94, v94
	v_exp_f32_e32 v95, v95
	v_pk_mul_f32 v[90:91], v[90:91], v[92:93]
	v_pk_mul_f32 v[92:93], v[86:87], v[98:99] op_sel_hi:[1,0]
	v_cvt_pk_bf16_f32 v88, v88, v89
	v_cvt_pk_bf16_f32 v89, v90, v91
	v_pk_add_f32 v[90:91], v[94:95], 1.0 op_sel_hi:[1,0]
	v_exp_f32_e32 v92, v92
	v_exp_f32_e32 v93, v93
	v_rcp_f32_e32 v90, v90
	v_rcp_f32_e32 v91, v91
	v_pk_mul_f32 v[80:81], v[84:85], v[80:81]
	v_pk_add_f32 v[84:85], v[92:93], 1.0 op_sel_hi:[1,0]
	v_pk_mul_f32 v[82:83], v[86:87], v[82:83]
; __device__ __forceinline__ unsigned cvt_pk_bf16(float lo, float hi) { unsigned r; asm volatile("v_cvt_pk_bf16_f32 %0, %1, %2" : "=v"(r) : "v"(lo), "v"(hi)); return r; }
;     __device__ __forceinline__ void operator()(const f32x4 (&acc)[2][2][4][2], const Unit& u, int ui, int wr, int wc, int fr, int fq) const {
;     ...
;             for (int m = 0; m < 4; ++m) { const float r = rs[ai][m]; const int row = row0 + ai * HALF + m * 16;
;                 const float c1 = r * -1.44269504089f, r2 = r * r; u32x4 w;
; #pragma unroll
;                 for (int n = 0; n < 2; ++n)
; #pragma unroll
;                     for (int p = 0; p < 2; ++p) { const f32x2 g = (f32x2){acc[ai][0][m][n][2 * p], acc[ai][0][m][n][2 * p + 1]}, uu = (f32x2){acc[ai][1][m][n][2 * p], acc[ai][1][m][n][2 * p + 1]};
;                         const f32x2 t = g * c1; f32x2 d; d.x = __builtin_amdgcn_exp2f(t.x); d.y = __builtin_amdgcn_exp2f(t.y); d = d + 1.0f;
;                         f32x2 q; q.x = __builtin_amdgcn_rcpf(d.x); q.y = __builtin_amdgcn_rcpf(d.y);
;                         const f32x2 hh = (g * uu) * (q * r2); w[2 * n + p] = cvt_pk_bf16(hh.x, hh.y); }
;                 __builtin_nontemporal_store(w, (u32x4*)(H + (size_t)row * ldh + col0)); }
	v_rcp_f32_e32 v84, v84
	v_rcp_f32_e32 v85, v85
	v_pk_mul_f32 v[86:87], v[96:97], v[90:91] op_sel_hi:[0,1]
	v_pk_mul_f32 v[80:81], v[80:81], v[86:87]
	v_pk_mul_f32 v[72:73], v[76:77], v[72:73]
	v_cvt_pk_bf16_f32 v90, v80, v81
	v_pk_mul_f32 v[80:81], v[96:97], v[84:85] op_sel_hi:[0,1]
	v_pk_mul_f32 v[80:81], v[82:83], v[80:81]
	v_mul_f32_e32 v82, 0xbfb8aa3b, v163
	v_pk_mul_f32 v[84:85], v[76:77], v[82:83] op_sel_hi:[1,0]
	v_pk_mul_f32 v[76:77], v[78:79], v[82:83] op_sel_hi:[1,0]
	v_exp_f32_e32 v84, v84
	v_exp_f32_e32 v85, v85
	v_exp_f32_e32 v76, v76
	v_exp_f32_e32 v77, v77
	v_cvt_pk_bf16_f32 v91, v80, v81
	v_pk_add_f32 v[84:85], v[84:85], 1.0 op_sel_hi:[1,0]
	v_rcp_f32_e32 v84, v84
	v_rcp_f32_e32 v85, v85
	v_pk_add_f32 v[76:77], v[76:77], 1.0 op_sel_hi:[1,0]
	v_rcp_f32_e32 v76, v76
	v_rcp_f32_e32 v77, v77
	s_add_u32 s100, s20, 0x2c000
	s_addc_u32 s101, s21, 0
	global_store_dwordx4 v255, v[88:91], s[100:101] nt
	v_mul_f32_e32 v80, v163, v163
	v_pk_mul_f32 v[74:75], v[78:79], v[74:75]
	v_pk_mul_f32 v[78:79], v[80:81], v[84:85] op_sel_hi:[0,1]
	v_pk_mul_f32 v[72:73], v[72:73], v[78:79]
	v_pk_mul_f32 v[78:79], v[68:69], v[82:83] op_sel_hi:[1,0]
	v_pk_mul_f32 v[76:77], v[80:81], v[76:77] op_sel_hi:[0,1]
	v_exp_f32_e32 v78, v78
	v_exp_f32_e32 v79, v79
	v_pk_mul_f32 v[74:75], v[74:75], v[76:77]
	v_pk_mul_f32 v[76:77], v[70:71], v[82:83] op_sel_hi:[1,0]
	v_cvt_pk_bf16_f32 v72, v72, v73
	v_cvt_pk_bf16_f32 v73, v74, v75
	v_pk_add_f32 v[74:75], v[78:79], 1.0 op_sel_hi:[1,0]
	v_exp_f32_e32 v76, v76
	v_exp_f32_e32 v77, v77
	v_rcp_f32_e32 v74, v74
	v_rcp_f32_e32 v75, v75
	v_pk_mul_f32 v[64:65], v[68:69], v[64:65]
	v_pk_add_f32 v[68:69], v[76:77], 1.0 op_sel_hi:[1,0]
	v_pk_mul_f32 v[66:67], v[70:71], v[66:67]
	v_rcp_f32_e32 v68, v68
	v_rcp_f32_e32 v69, v69
	v_pk_mul_f32 v[70:71], v[80:81], v[74:75] op_sel_hi:[0,1]
	v_pk_mul_f32 v[64:65], v[64:65], v[70:71]
	v_pk_mul_f32 v[56:57], v[60:61], v[56:57]
	v_cvt_pk_bf16_f32 v74, v64, v65
	v_pk_mul_f32 v[64:65], v[80:81], v[68:69] op_sel_hi:[0,1]
	v_pk_mul_f32 v[64:65], v[66:67], v[64:65]
	v_mul_f32_e32 v66, 0xbfb8aa3b, v142
	v_pk_mul_f32 v[68:69], v[60:61], v[66:67] op_sel_hi:[1,0]
	v_pk_mul_f32 v[60:61], v[62:63], v[66:67] op_sel_hi:[1,0]
	v_exp_f32_e32 v68, v68
	v_exp_f32_e32 v69, v69
	v_exp_f32_e32 v60, v60
	v_exp_f32_e32 v61, v61
	v_cvt_pk_bf16_f32 v75, v64, v65
	v_pk_add_f32 v[68:69], v[68:69], 1.0 op_sel_hi:[1,0]
	v_rcp_f32_e32 v68, v68
	v_rcp_f32_e32 v69, v69
	v_pk_add_f32 v[60:61], v[60:61], 1.0 op_sel_hi:[1,0]
	v_rcp_f32_e32 v60, v60
	v_rcp_f32_e32 v61, v61
	s_add_u32 s100, s20, 0x42000
	s_addc_u32 s101, s21, 0
	global_store_dwordx4 v255, v[72:75], s[100:101] nt
	v_mul_f32_e32 v64, v142, v142
	v_pk_mul_f32 v[58:59], v[62:63], v[58:59]
	v_pk_mul_f32 v[62:63], v[64:65], v[68:69] op_sel_hi:[0,1]
	v_pk_mul_f32 v[56:57], v[56:57], v[62:63]
	v_pk_mul_f32 v[62:63], v[52:53], v[66:67] op_sel_hi:[1,0]
	v_pk_mul_f32 v[60:61], v[64:65], v[60:61] op_sel_hi:[0,1]
	v_exp_f32_e32 v62, v62
	v_exp_f32_e32 v63, v63
	v_pk_mul_f32 v[58:59], v[58:59], v[60:61]
	v_pk_mul_f32 v[60:61], v[54:55], v[66:67] op_sel_hi:[1,0]
	v_cvt_pk_bf16_f32 v56, v56, v57
	v_cvt_pk_bf16_f32 v57, v58, v59
	v_pk_add_f32 v[58:59], v[62:63], 1.0 op_sel_hi:[1,0]
	v_exp_f32_e32 v60, v60
	v_exp_f32_e32 v61, v61
	v_rcp_f32_e32 v58, v58
	v_rcp_f32_e32 v59, v59
	v_pk_mul_f32 v[48:49], v[52:53], v[48:49]
	v_pk_add_f32 v[52:53], v[60:61], 1.0 op_sel_hi:[1,0]
	v_pk_mul_f32 v[50:51], v[54:55], v[50:51]
	v_rcp_f32_e32 v52, v52
	v_rcp_f32_e32 v53, v53
	v_pk_mul_f32 v[54:55], v[64:65], v[58:59] op_sel_hi:[0,1]
	v_pk_mul_f32 v[48:49], v[48:49], v[54:55]
	v_pk_mul_f32 v[40:41], v[44:45], v[40:41]
	v_cvt_pk_bf16_f32 v58, v48, v49
	v_pk_mul_f32 v[48:49], v[64:65], v[52:53] op_sel_hi:[0,1]
	v_pk_mul_f32 v[48:49], v[50:51], v[48:49]
	v_mul_f32_e32 v50, 0xbfb8aa3b, v143
	v_pk_mul_f32 v[52:53], v[44:45], v[50:51] op_sel_hi:[1,0]
	v_pk_mul_f32 v[44:45], v[46:47], v[50:51] op_sel_hi:[1,0]
	v_exp_f32_e32 v52, v52
	v_exp_f32_e32 v53, v53
	v_exp_f32_e32 v44, v44
	v_exp_f32_e32 v45, v45
	v_cvt_pk_bf16_f32 v59, v48, v49
	v_pk_add_f32 v[52:53], v[52:53], 1.0 op_sel_hi:[1,0]
	v_rcp_f32_e32 v52, v52
	v_rcp_f32_e32 v53, v53
	v_pk_add_f32 v[44:45], v[44:45], 1.0 op_sel_hi:[1,0]
	v_rcp_f32_e32 v44, v44
	v_rcp_f32_e32 v45, v45
	s_add_u32 s100, s20, 0xb0000
	s_addc_u32 s101, s21, 0
	global_store_dwordx4 v255, v[56:59], s[100:101] nt
	v_mul_f32_e32 v48, v143, v143
	v_pk_mul_f32 v[42:43], v[46:47], v[42:43]
	v_pk_mul_f32 v[46:47], v[48:49], v[52:53] op_sel_hi:[0,1]
	v_pk_mul_f32 v[40:41], v[40:41], v[46:47]
	v_pk_mul_f32 v[46:47], v[36:37], v[50:51] op_sel_hi:[1,0]
; __device__ __forceinline__ unsigned cvt_pk_bf16(float lo, float hi) { unsigned r; asm volatile("v_cvt_pk_bf16_f32 %0, %1, %2" : "=v"(r) : "v"(lo), "v"(hi)); return r; }
; #define PG8_BAR __builtin_amdgcn_s_barrier()
;     __device__ __forceinline__ void operator()(const f32x4 (&acc)[2][2][4][2], const Unit& u, int ui, int wr, int wc, int fr, int fq) const {
;     ...
;             for (int m = 0; m < 4; ++m) { const float r = rs[ai][m]; const int row = row0 + ai * HALF + m * 16;
;                 const float c1 = r * -1.44269504089f, r2 = r * r; u32x4 w;
; #pragma unroll
;                 for (int n = 0; n < 2; ++n)
; #pragma unroll
;                     for (int p = 0; p < 2; ++p) { const f32x2 g = (f32x2){acc[ai][0][m][n][2 * p], acc[ai][0][m][n][2 * p + 1]}, uu = (f32x2){acc[ai][1][m][n][2 * p], acc[ai][1][m][n][2 * p + 1]};
;                         const f32x2 t = g * c1; f32x2 d; d.x = __builtin_amdgcn_exp2f(t.x); d.y = __builtin_amdgcn_exp2f(t.y); d = d + 1.0f;
;                         f32x2 q; q.x = __builtin_amdgcn_rcpf(d.x); q.y = __builtin_amdgcn_rcpf(d.y);
;                         const f32x2 hh = (g * uu) * (q * r2); w[2 * n + p] = cvt_pk_bf16(hh.x, hh.y); }
;                 __builtin_nontemporal_store(w, (u32x4*)(H + (size_t)row * ldh + col0)); }
; template <class Epi, class Sched, bool ALIGN_EPI = false, bool SP2 = false>
; __device__ __forceinline__ void gemm_phase(PG8_LAS unsigned char* lds, const Gemm g, const Sched& S, const Epi& E) {
;     ...
;         if constexpr (!Epi::AFTER_DRAIN) { E(acc, cur, ui, wr, wc, fr, fq); S.done(cur); }
;         if (!has_next) break;
; #pragma unroll
;         for (int a = 0; a < 2; ++a)
; #pragma unroll
;             for (int b = 0; b < 2; ++b)
; #pragma unroll
;                 for (int m = 0; m < 4; ++m)
; #pragma unroll
;                     for (int n = 0; n < 2; ++n) acc[a][b][m][n] = (f32x4){0.f, 0.f, 0.f, 0.f};
;         cur = nxt; cA = nA; cB = nB; ++ui;
;         if constexpr (ALIGN_EPI) { if (wr == 1) PG8_BAR; }
	v_pk_mul_f32 v[44:45], v[48:49], v[44:45] op_sel_hi:[0,1]
	v_exp_f32_e32 v46, v46
	v_exp_f32_e32 v47, v47
	v_pk_mul_f32 v[42:43], v[42:43], v[44:45]
	v_pk_mul_f32 v[44:45], v[38:39], v[50:51] op_sel_hi:[1,0]
	v_cvt_pk_bf16_f32 v40, v40, v41
	v_cvt_pk_bf16_f32 v41, v42, v43
	v_pk_add_f32 v[42:43], v[46:47], 1.0 op_sel_hi:[1,0]
	v_exp_f32_e32 v44, v44
	v_exp_f32_e32 v45, v45
	v_rcp_f32_e32 v42, v42
	v_rcp_f32_e32 v43, v43
	v_pk_mul_f32 v[32:33], v[36:37], v[32:33]
	v_pk_add_f32 v[36:37], v[44:45], 1.0 op_sel_hi:[1,0]
	v_pk_mul_f32 v[34:35], v[38:39], v[34:35]
	v_rcp_f32_e32 v36, v36
	v_rcp_f32_e32 v37, v37
	v_pk_mul_f32 v[38:39], v[48:49], v[42:43] op_sel_hi:[0,1]
	v_pk_mul_f32 v[32:33], v[32:33], v[38:39]
	v_pk_mul_f32 v[24:25], v[28:29], v[24:25]
	v_cvt_pk_bf16_f32 v42, v32, v33
	v_pk_mul_f32 v[32:33], v[48:49], v[36:37] op_sel_hi:[0,1]
	v_pk_mul_f32 v[32:33], v[34:35], v[32:33]
	v_mul_f32_e32 v34, 0xbfb8aa3b, v140
	v_pk_mul_f32 v[36:37], v[28:29], v[34:35] op_sel_hi:[1,0]
	v_pk_mul_f32 v[28:29], v[30:31], v[34:35] op_sel_hi:[1,0]
	v_exp_f32_e32 v36, v36
	v_exp_f32_e32 v37, v37
	v_exp_f32_e32 v28, v28
	v_exp_f32_e32 v29, v29
	v_cvt_pk_bf16_f32 v43, v32, v33
	v_pk_add_f32 v[36:37], v[36:37], 1.0 op_sel_hi:[1,0]
	v_rcp_f32_e32 v36, v36
	v_rcp_f32_e32 v37, v37
	v_pk_add_f32 v[28:29], v[28:29], 1.0 op_sel_hi:[1,0]
	v_rcp_f32_e32 v28, v28
	v_rcp_f32_e32 v29, v29
	s_add_u32 s100, s20, 0xc6000
	s_addc_u32 s101, s21, 0
	global_store_dwordx4 v255, v[40:43], s[100:101] nt
	v_mul_f32_e32 v32, v140, v140
	v_pk_mul_f32 v[26:27], v[30:31], v[26:27]
	v_pk_mul_f32 v[30:31], v[32:33], v[36:37] op_sel_hi:[0,1]
	v_pk_mul_f32 v[24:25], v[24:25], v[30:31]
	v_pk_mul_f32 v[30:31], v[20:21], v[34:35] op_sel_hi:[1,0]
	v_pk_mul_f32 v[28:29], v[32:33], v[28:29] op_sel_hi:[0,1]
	v_exp_f32_e32 v30, v30
	v_exp_f32_e32 v31, v31
	v_pk_mul_f32 v[26:27], v[26:27], v[28:29]
	v_pk_mul_f32 v[28:29], v[22:23], v[34:35] op_sel_hi:[1,0]
	v_cvt_pk_bf16_f32 v24, v24, v25
	v_cvt_pk_bf16_f32 v25, v26, v27
	v_pk_add_f32 v[26:27], v[30:31], 1.0 op_sel_hi:[1,0]
	v_exp_f32_e32 v28, v28
	v_exp_f32_e32 v29, v29
	v_rcp_f32_e32 v26, v26
	v_rcp_f32_e32 v27, v27
	v_pk_mul_f32 v[16:17], v[20:21], v[16:17]
	v_pk_add_f32 v[20:21], v[28:29], 1.0 op_sel_hi:[1,0]
	v_pk_mul_f32 v[18:19], v[22:23], v[18:19]
	v_rcp_f32_e32 v20, v20
	v_rcp_f32_e32 v21, v21
	v_pk_mul_f32 v[22:23], v[32:33], v[26:27] op_sel_hi:[0,1]
	v_pk_mul_f32 v[16:17], v[16:17], v[22:23]
	v_pk_mul_f32 v[8:9], v[12:13], v[8:9]
	v_cvt_pk_bf16_f32 v26, v16, v17
	v_pk_mul_f32 v[16:17], v[32:33], v[20:21] op_sel_hi:[0,1]
	v_pk_mul_f32 v[16:17], v[18:19], v[16:17]
	v_mul_f32_e32 v18, 0xbfb8aa3b, v141
	v_pk_mul_f32 v[20:21], v[12:13], v[18:19] op_sel_hi:[1,0]
	v_pk_mul_f32 v[12:13], v[14:15], v[18:19] op_sel_hi:[1,0]
	v_exp_f32_e32 v20, v20
	v_exp_f32_e32 v21, v21
	v_exp_f32_e32 v12, v12
	v_exp_f32_e32 v13, v13
	v_cvt_pk_bf16_f32 v27, v16, v17
	v_pk_add_f32 v[20:21], v[20:21], 1.0 op_sel_hi:[1,0]
	v_rcp_f32_e32 v20, v20
	v_rcp_f32_e32 v21, v21
	v_pk_add_f32 v[12:13], v[12:13], 1.0 op_sel_hi:[1,0]
	v_rcp_f32_e32 v12, v12
	v_rcp_f32_e32 v13, v13
	s_add_u32 s100, s20, 0xdc000
	s_addc_u32 s101, s21, 0
	global_store_dwordx4 v255, v[24:27], s[100:101] nt
	v_mul_f32_e32 v16, v141, v141
	v_pk_mul_f32 v[10:11], v[14:15], v[10:11]
	v_pk_mul_f32 v[14:15], v[16:17], v[20:21] op_sel_hi:[0,1]
	v_pk_mul_f32 v[8:9], v[8:9], v[14:15]
	v_pk_mul_f32 v[14:15], v[4:5], v[18:19] op_sel_hi:[1,0]
	v_pk_mul_f32 v[12:13], v[16:17], v[12:13] op_sel_hi:[0,1]
	v_exp_f32_e32 v14, v14
	v_exp_f32_e32 v15, v15
	v_pk_mul_f32 v[10:11], v[10:11], v[12:13]
	v_pk_mul_f32 v[12:13], v[6:7], v[18:19] op_sel_hi:[1,0]
	v_cvt_pk_bf16_f32 v8, v8, v9
	v_cvt_pk_bf16_f32 v9, v10, v11
	v_pk_add_f32 v[10:11], v[14:15], 1.0 op_sel_hi:[1,0]
	v_exp_f32_e32 v12, v12
	v_exp_f32_e32 v13, v13
	v_rcp_f32_e32 v10, v10
	v_rcp_f32_e32 v11, v11
	v_pk_mul_f32 v[0:1], v[4:5], v[0:1]
	v_pk_add_f32 v[4:5], v[12:13], 1.0 op_sel_hi:[1,0]
	v_pk_mul_f32 v[2:3], v[6:7], v[2:3]
	v_rcp_f32_e32 v4, v4
	v_rcp_f32_e32 v5, v5
	v_pk_mul_f32 v[6:7], v[16:17], v[10:11] op_sel_hi:[0,1]
	v_pk_mul_f32 v[0:1], v[0:1], v[6:7]
	s_andn2_b64 vcc, exec, s[8:9]
	v_cvt_pk_bf16_f32 v10, v0, v1
	v_pk_mul_f32 v[0:1], v[16:17], v[4:5] op_sel_hi:[0,1]
	v_pk_mul_f32 v[0:1], v[2:3], v[0:1]
	s_mov_b64 s[8:9], -1
	v_cvt_pk_bf16_f32 v11, v0, v1
	s_add_u32 s100, s20, 0xf2000
	s_addc_u32 s101, s21, 0
	global_store_dwordx4 v255, v[8:11], s[100:101] nt
	s_cbranch_vccnz .LBB0_442
	s_andn2_b64 vcc, exec, s[0:1]
	s_cbranch_vccnz .LBB0_441
	s_barrier
	s_branch .LBB0_441
